# P8 swiglu+norm epilogue hand-written (packed f32, rstd LDS reads two rows in flight)
# baseline (speedup 1.0000x reference)
; #define PG8_LAS __attribute__((address_space(3)))
; #define EPI_ROWS _Pragma("unroll") for (int ai = 0; ai < 2; ++ai) _Pragma("unroll") for (int m = 0; m < 4; ++m)
; __device__ __forceinline__ float rstd_lds(const PG8_LAS unsigned char* scr, int lrow) {
;     const PG8_LAS f32x4* p = (const PG8_LAS f32x4*)(scr + lrow * 64);
;     const f32x4 s = (p[0] + p[1]) + (p[2] + p[3]);
;     return __builtin_amdgcn_rsqf(((s[0] + s[1]) + (s[2] + s[3])) * (1.0f / DM) + RMS_EPS);
; }
;     __device__ __forceinline__ void operator()(const f32x4 (&acc)[2][2][4][2], const Unit& u, int wr, int wc, int fr, int fq) const {
;     ...
;         if (NORM) { const PG8_LAS float* bp = (const PG8_LAS float*)(scr + 16384) + tcol; ba0 = *(const PG8_LAS f32x4*)bp; ba1 = *(const PG8_LAS f32x4*)(bp + 4); bb0 = *(const PG8_LAS f32x4*)(bp + HALF); bb1 = *(const PG8_LAS f32x4*)(bp + HALF + 4); }
;         float rsv[2][4];
;         if (NORM) { EPI_ROWS { rsv[ai][m] = rstd_lds(scr, EPI_LROW); asm volatile("" : "+v"(rsv[ai][m]) :: "memory"); } }
.LBB0_991:
	v_mov_b32_e32 v138, 0xbfb8aa3b
	v_mov_b32_e32 v139, 0xbfb8aa3b
	v_mov_b32_e32 v140, 0x358637bd
	v_lshlrev_b32_e32 v141, 6, v1
	v_lshl_add_u32 v168, v192, 5, s70
	ds_read_b128 v[200:203], v168
	ds_read_b128 v[204:207], v168 offset:16
	ds_read_b128 v[208:211], v168 offset:512
	ds_read_b128 v[212:215], v168 offset:528
	v_add_u32_e32 v169, s71, v141
	ds_read_b128 v[216:219], v169
	ds_read_b128 v[220:223], v169 offset:16
	ds_read_b128 v[224:227], v169 offset:32
	ds_read_b128 v[228:231], v169 offset:48
	v_add_u32_e32 v169, s72, v141
	ds_read_b128 v[160:163], v169
	ds_read_b128 v[164:167], v169 offset:16
	ds_read_b128 v[98:101], v169 offset:32
	ds_read_b128 v[106:109], v169 offset:48
	s_waitcnt lgkmcnt(4)
	v_pk_add_f32 v[218:219], v[218:219], v[222:223]
	v_pk_add_f32 v[216:217], v[216:217], v[220:221]
	v_pk_add_f32 v[220:221], v[226:227], v[230:231]
	v_pk_add_f32 v[222:223], v[224:225], v[228:229]
	v_pk_add_f32 v[218:219], v[218:219], v[220:221]
	v_pk_add_f32 v[216:217], v[216:217], v[222:223]
	v_add_f32_e32 v216, v216, v217
	v_add_f32_e32 v218, v218, v219
	v_add_f32_e32 v216, v216, v218
	v_fmamk_f32 v216, v216, 0x3a800000, v140
	v_rsq_f32_e32 v142, v216
	s_waitcnt lgkmcnt(0)
	v_pk_add_f32 v[162:163], v[162:163], v[166:167]
	v_pk_add_f32 v[160:161], v[160:161], v[164:165]
	v_pk_add_f32 v[164:165], v[100:101], v[108:109]
	v_pk_add_f32 v[166:167], v[98:99], v[106:107]
	v_pk_add_f32 v[162:163], v[162:163], v[164:165]
	v_pk_add_f32 v[160:161], v[160:161], v[166:167]
	v_add_f32_e32 v160, v160, v161
	v_add_f32_e32 v162, v162, v163
	v_add_f32_e32 v160, v160, v162
	v_fmamk_f32 v160, v160, 0x3a800000, v140
	v_rsq_f32_e32 v144, v160
	v_add_u32_e32 v169, s73, v141
	ds_read_b128 v[216:219], v169
	ds_read_b128 v[220:223], v169 offset:16
	ds_read_b128 v[224:227], v169 offset:32
	ds_read_b128 v[228:231], v169 offset:48
	v_add_u32_e32 v169, s74, v141
	ds_read_b128 v[160:163], v169
	ds_read_b128 v[164:167], v169 offset:16
	ds_read_b128 v[98:101], v169 offset:32
	ds_read_b128 v[106:109], v169 offset:48
	s_waitcnt lgkmcnt(4)
	v_pk_add_f32 v[218:219], v[218:219], v[222:223]
	v_pk_add_f32 v[216:217], v[216:217], v[220:221]
	v_pk_add_f32 v[220:221], v[226:227], v[230:231]
	v_pk_add_f32 v[222:223], v[224:225], v[228:229]
	v_pk_add_f32 v[218:219], v[218:219], v[220:221]
	v_pk_add_f32 v[216:217], v[216:217], v[222:223]
	v_add_f32_e32 v216, v216, v217
	v_add_f32_e32 v218, v218, v219
	v_add_f32_e32 v216, v216, v218
	v_fmamk_f32 v216, v216, 0x3a800000, v140
	v_rsq_f32_e32 v146, v216
	s_waitcnt lgkmcnt(0)
	v_pk_add_f32 v[162:163], v[162:163], v[166:167]
	v_pk_add_f32 v[160:161], v[160:161], v[164:165]
	v_pk_add_f32 v[164:165], v[100:101], v[108:109]
	v_pk_add_f32 v[166:167], v[98:99], v[106:107]
	v_pk_add_f32 v[162:163], v[162:163], v[164:165]
	v_pk_add_f32 v[160:161], v[160:161], v[166:167]
	v_add_f32_e32 v160, v160, v161
	v_add_f32_e32 v162, v162, v163
	v_add_f32_e32 v160, v160, v162
	v_fmamk_f32 v160, v160, 0x3a800000, v140
	v_rsq_f32_e32 v148, v160
	v_add_u32_e32 v169, s75, v141
	ds_read_b128 v[216:219], v169
	ds_read_b128 v[220:223], v169 offset:16
	ds_read_b128 v[224:227], v169 offset:32
	ds_read_b128 v[228:231], v169 offset:48
	v_add_u32_e32 v169, s76, v141
	ds_read_b128 v[160:163], v169
	ds_read_b128 v[164:167], v169 offset:16
	ds_read_b128 v[98:101], v169 offset:32
	ds_read_b128 v[106:109], v169 offset:48
	s_waitcnt lgkmcnt(4)
	v_pk_add_f32 v[218:219], v[218:219], v[222:223]
	v_pk_add_f32 v[216:217], v[216:217], v[220:221]
	v_pk_add_f32 v[220:221], v[226:227], v[230:231]
	v_pk_add_f32 v[222:223], v[224:225], v[228:229]
	v_pk_add_f32 v[218:219], v[218:219], v[220:221]
	v_pk_add_f32 v[216:217], v[216:217], v[222:223]
	v_add_f32_e32 v216, v216, v217
	v_add_f32_e32 v218, v218, v219
	v_add_f32_e32 v216, v216, v218
	v_fmamk_f32 v216, v216, 0x3a800000, v140
	v_rsq_f32_e32 v150, v216
	s_waitcnt lgkmcnt(0)
	v_pk_add_f32 v[162:163], v[162:163], v[166:167]
	v_pk_add_f32 v[160:161], v[160:161], v[164:165]
	v_pk_add_f32 v[164:165], v[100:101], v[108:109]
	v_pk_add_f32 v[166:167], v[98:99], v[106:107]
	v_pk_add_f32 v[162:163], v[162:163], v[164:165]
	v_pk_add_f32 v[160:161], v[160:161], v[166:167]
	v_add_f32_e32 v160, v160, v161
	v_add_f32_e32 v162, v162, v163
	v_add_f32_e32 v160, v160, v162
	v_fmamk_f32 v160, v160, 0x3a800000, v140
	v_rsq_f32_e32 v152, v160
	v_add_u32_e32 v169, s77, v141
	ds_read_b128 v[216:219], v169
	ds_read_b128 v[220:223], v169 offset:16
	ds_read_b128 v[224:227], v169 offset:32
	ds_read_b128 v[228:231], v169 offset:48
	v_add_u32_e32 v169, s78, v141
	ds_read_b128 v[160:163], v169
	ds_read_b128 v[164:167], v169 offset:16
	ds_read_b128 v[98:101], v169 offset:32
	ds_read_b128 v[106:109], v169 offset:48
	s_waitcnt lgkmcnt(4)
	v_pk_add_f32 v[218:219], v[218:219], v[222:223]
	v_pk_add_f32 v[216:217], v[216:217], v[220:221]
	v_pk_add_f32 v[220:221], v[226:227], v[230:231]
	v_pk_add_f32 v[222:223], v[224:225], v[228:229]
	v_pk_add_f32 v[218:219], v[218:219], v[220:221]
	v_pk_add_f32 v[216:217], v[216:217], v[222:223]
	v_add_f32_e32 v216, v216, v217
	v_add_f32_e32 v218, v218, v219
	v_add_f32_e32 v216, v216, v218
	v_fmamk_f32 v216, v216, 0x3a800000, v140
	v_rsq_f32_e32 v154, v216
	s_waitcnt lgkmcnt(0)
; __device__ __forceinline__ u32x4 pack8(const f32x4 a, const f32x4 b) { u32x4 w; w.x = cvt_pk_bf16(a[0], a[1]); w.y = cvt_pk_bf16(a[2], a[3]); w.z = cvt_pk_bf16(b[0], b[1]); w.w = cvt_pk_bf16(b[2], b[3]); return w; }
; __device__ __forceinline__ float sigm(float v) { return __builtin_amdgcn_rcpf(1.f + __expf(-v)); }
; #define EPI_ROWS _Pragma("unroll") for (int ai = 0; ai < 2; ++ai) _Pragma("unroll") for (int m = 0; m < 4; ++m)
;     __device__ __forceinline__ void operator()(const f32x4 (&acc)[2][2][4][2], const Unit& u, int wr, int wc, int fr, int fq) const {
;     ...
;         if (NORM) { EPI_ROWS { rsv[ai][m] = rstd_lds(scr, EPI_LROW); asm volatile("" : "+v"(rsv[ai][m]) :: "memory"); } }
;         EPI_ROWS { const int row = EPI_ROW;
;             f32x4 a0 = acc[ai][0][m][0], a1 = acc[ai][0][m][1], b0 = acc[ai][1][m][0], b1 = acc[ai][1][m][1];
;             if (NORM) { const float rs = rsv[ai][m]; a0 = a0 * rs + ba0; a1 = a1 * rs + ba1; b0 = b0 * rs + bb0; b1 = b1 * rs + bb1; }
;             f32x4 o0, o1;
; #pragma unroll
;             for (int i = 0; i < 4; ++i) { o0[i] = a0[i] * sigm(a0[i]) * b0[i]; o1[i] = a1[i] * sigm(a1[i]) * b1[i]; }
;             *(u32x4*)(act + (size_t)(row >> 1) * (2 * DFF) + (u.pn * 4 + wc) * 64 + (row & 1) * 32 + fq * 8) = pack8(o0, o1); }
	v_pk_add_f32 v[162:163], v[162:163], v[166:167]
	v_pk_add_f32 v[160:161], v[160:161], v[164:165]
	v_pk_add_f32 v[164:165], v[100:101], v[108:109]
	v_pk_add_f32 v[166:167], v[98:99], v[106:107]
	v_pk_add_f32 v[162:163], v[162:163], v[164:165]
	v_pk_add_f32 v[160:161], v[160:161], v[166:167]
	v_add_f32_e32 v160, v160, v161
	v_add_f32_e32 v162, v162, v163
	v_add_f32_e32 v160, v160, v162
	v_fmamk_f32 v160, v160, 0x3a800000, v140
	v_rsq_f32_e32 v156, v160
	v_lshrrev_b32_e32 v168, 1, v1
	v_mul_u32_u24_e32 v168, 0x2c00, v168
	v_and_b32_e32 v169, 1, v1
	v_lshl_add_u32 v168, v169, 6, v168
	v_lshl_add_u32 v168, v192, 4, v168
	s_lshl_b32 s21, s28, 8
	s_add_i32 s21, s21, s64
	s_lshr_b32 s21, s21, 1
	s_mul_i32 s21, s21, 0x2c00
	s_or_b32 s28, s34, s67
	s_lshl_b32 s28, s28, 1
	s_add_u32 s21, s21, s28
	s_add_u32 s28, s6, s21
	s_addc_u32 s29, s7, 0
	v_pk_fma_f32 v[134:135], v[134:135], v[142:143], v[200:201] op_sel_hi:[1,0,1]
	v_pk_fma_f32 v[136:137], v[136:137], v[142:143], v[202:203] op_sel_hi:[1,0,1]
	v_pk_fma_f32 v[130:131], v[130:131], v[142:143], v[204:205] op_sel_hi:[1,0,1]
	v_pk_fma_f32 v[132:133], v[132:133], v[142:143], v[206:207] op_sel_hi:[1,0,1]
	v_pk_fma_f32 v[126:127], v[126:127], v[142:143], v[208:209] op_sel_hi:[1,0,1]
	v_pk_fma_f32 v[128:129], v[128:129], v[142:143], v[210:211] op_sel_hi:[1,0,1]
	v_pk_fma_f32 v[122:123], v[122:123], v[142:143], v[212:213] op_sel_hi:[1,0,1]
	v_pk_fma_f32 v[124:125], v[124:125], v[142:143], v[214:215] op_sel_hi:[1,0,1]
	v_pk_mul_f32 v[216:217], v[138:139], v[134:135]
	v_pk_mul_f32 v[218:219], v[138:139], v[136:137]
	v_pk_mul_f32 v[220:221], v[138:139], v[130:131]
	v_pk_mul_f32 v[222:223], v[138:139], v[132:133]
	v_exp_f32_e32 v216, v216
	v_exp_f32_e32 v217, v217
	v_exp_f32_e32 v218, v218
	v_exp_f32_e32 v219, v219
	v_exp_f32_e32 v220, v220
	v_exp_f32_e32 v221, v221
	v_exp_f32_e32 v222, v222
	v_exp_f32_e32 v223, v223
	v_pk_add_f32 v[216:217], v[216:217], 1.0 op_sel_hi:[1,0]
	v_pk_add_f32 v[218:219], v[218:219], 1.0 op_sel_hi:[1,0]
	v_pk_add_f32 v[220:221], v[220:221], 1.0 op_sel_hi:[1,0]
	v_pk_add_f32 v[222:223], v[222:223], 1.0 op_sel_hi:[1,0]
	v_rcp_f32_e32 v216, v216
	v_rcp_f32_e32 v217, v217
	v_rcp_f32_e32 v218, v218
	v_rcp_f32_e32 v219, v219
	v_rcp_f32_e32 v220, v220
	v_rcp_f32_e32 v221, v221
	v_rcp_f32_e32 v222, v222
	v_rcp_f32_e32 v223, v223
	v_pk_mul_f32 v[216:217], v[134:135], v[216:217]
	v_pk_mul_f32 v[218:219], v[136:137], v[218:219]
	v_pk_mul_f32 v[220:221], v[130:131], v[220:221]
	v_pk_mul_f32 v[222:223], v[132:133], v[222:223]
	v_pk_mul_f32 v[216:217], v[216:217], v[126:127]
	v_pk_mul_f32 v[218:219], v[218:219], v[128:129]
	v_pk_mul_f32 v[220:221], v[220:221], v[122:123]
	v_pk_mul_f32 v[222:223], v[222:223], v[124:125]
	v_cvt_pk_bf16_f32 v160, v216, v217
	v_cvt_pk_bf16_f32 v161, v218, v219
	v_cvt_pk_bf16_f32 v162, v220, v221
	v_cvt_pk_bf16_f32 v163, v222, v223
	global_store_dwordx4 v168, v[160:163], s[28:29]
	s_add_u32 s28, s28, 0x16000
	s_addc_u32 s29, s29, 0
	v_pk_fma_f32 v[118:119], v[118:119], v[144:145], v[200:201] op_sel_hi:[1,0,1]
	v_pk_fma_f32 v[120:121], v[120:121], v[144:145], v[202:203] op_sel_hi:[1,0,1]
	v_pk_fma_f32 v[114:115], v[114:115], v[144:145], v[204:205] op_sel_hi:[1,0,1]
	v_pk_fma_f32 v[116:117], v[116:117], v[144:145], v[206:207] op_sel_hi:[1,0,1]
	v_pk_fma_f32 v[110:111], v[110:111], v[144:145], v[208:209] op_sel_hi:[1,0,1]
	v_pk_fma_f32 v[112:113], v[112:113], v[144:145], v[210:211] op_sel_hi:[1,0,1]
	v_pk_fma_f32 v[102:103], v[102:103], v[144:145], v[212:213] op_sel_hi:[1,0,1]
	v_pk_fma_f32 v[104:105], v[104:105], v[144:145], v[214:215] op_sel_hi:[1,0,1]
	v_pk_mul_f32 v[224:225], v[138:139], v[118:119]
	v_pk_mul_f32 v[226:227], v[138:139], v[120:121]
	v_pk_mul_f32 v[228:229], v[138:139], v[114:115]
	v_pk_mul_f32 v[230:231], v[138:139], v[116:117]
	v_exp_f32_e32 v224, v224
	v_exp_f32_e32 v225, v225
	v_exp_f32_e32 v226, v226
	v_exp_f32_e32 v227, v227
	v_exp_f32_e32 v228, v228
	v_exp_f32_e32 v229, v229
	v_exp_f32_e32 v230, v230
	v_exp_f32_e32 v231, v231
	v_pk_add_f32 v[224:225], v[224:225], 1.0 op_sel_hi:[1,0]
	v_pk_add_f32 v[226:227], v[226:227], 1.0 op_sel_hi:[1,0]
	v_pk_add_f32 v[228:229], v[228:229], 1.0 op_sel_hi:[1,0]
	v_pk_add_f32 v[230:231], v[230:231], 1.0 op_sel_hi:[1,0]
	v_rcp_f32_e32 v224, v224
	v_rcp_f32_e32 v225, v225
	v_rcp_f32_e32 v226, v226
	v_rcp_f32_e32 v227, v227
	v_rcp_f32_e32 v228, v228
	v_rcp_f32_e32 v229, v229
	v_rcp_f32_e32 v230, v230
	v_rcp_f32_e32 v231, v231
	v_pk_mul_f32 v[224:225], v[118:119], v[224:225]
	v_pk_mul_f32 v[226:227], v[120:121], v[226:227]
	v_pk_mul_f32 v[228:229], v[114:115], v[228:229]
	v_pk_mul_f32 v[230:231], v[116:117], v[230:231]
	v_pk_mul_f32 v[224:225], v[224:225], v[110:111]
	v_pk_mul_f32 v[226:227], v[226:227], v[112:113]
	v_pk_mul_f32 v[228:229], v[228:229], v[102:103]
	v_pk_mul_f32 v[230:231], v[230:231], v[104:105]
	v_cvt_pk_bf16_f32 v164, v224, v225
	v_cvt_pk_bf16_f32 v165, v226, v227
	v_cvt_pk_bf16_f32 v166, v228, v229
	v_cvt_pk_bf16_f32 v167, v230, v231
	global_store_dwordx4 v168, v[164:167], s[28:29]
	s_add_u32 s28, s28, 0x16000
	s_addc_u32 s29, s29, 0
	v_pk_fma_f32 v[94:95], v[94:95], v[146:147], v[200:201] op_sel_hi:[1,0,1]
	v_pk_fma_f32 v[96:97], v[96:97], v[146:147], v[202:203] op_sel_hi:[1,0,1]
	v_pk_fma_f32 v[90:91], v[90:91], v[146:147], v[204:205] op_sel_hi:[1,0,1]
	v_pk_fma_f32 v[92:93], v[92:93], v[146:147], v[206:207] op_sel_hi:[1,0,1]
	v_pk_fma_f32 v[86:87], v[86:87], v[146:147], v[208:209] op_sel_hi:[1,0,1]
	v_pk_fma_f32 v[88:89], v[88:89], v[146:147], v[210:211] op_sel_hi:[1,0,1]
	v_pk_fma_f32 v[82:83], v[82:83], v[146:147], v[212:213] op_sel_hi:[1,0,1]
	v_pk_fma_f32 v[84:85], v[84:85], v[146:147], v[214:215] op_sel_hi:[1,0,1]
; __device__ __forceinline__ u32x4 pack8(const f32x4 a, const f32x4 b) { u32x4 w; w.x = cvt_pk_bf16(a[0], a[1]); w.y = cvt_pk_bf16(a[2], a[3]); w.z = cvt_pk_bf16(b[0], b[1]); w.w = cvt_pk_bf16(b[2], b[3]); return w; }
; __device__ __forceinline__ float sigm(float v) { return __builtin_amdgcn_rcpf(1.f + __expf(-v)); }
; #define EPI_ROWS _Pragma("unroll") for (int ai = 0; ai < 2; ++ai) _Pragma("unroll") for (int m = 0; m < 4; ++m)
;     __device__ __forceinline__ void operator()(const f32x4 (&acc)[2][2][4][2], const Unit& u, int wr, int wc, int fr, int fq) const {
;     ...
;         EPI_ROWS { const int row = EPI_ROW;
;             f32x4 a0 = acc[ai][0][m][0], a1 = acc[ai][0][m][1], b0 = acc[ai][1][m][0], b1 = acc[ai][1][m][1];
;             if (NORM) { const float rs = rsv[ai][m]; a0 = a0 * rs + ba0; a1 = a1 * rs + ba1; b0 = b0 * rs + bb0; b1 = b1 * rs + bb1; }
;             f32x4 o0, o1;
; #pragma unroll
;             for (int i = 0; i < 4; ++i) { o0[i] = a0[i] * sigm(a0[i]) * b0[i]; o1[i] = a1[i] * sigm(a1[i]) * b1[i]; }
;             *(u32x4*)(act + (size_t)(row >> 1) * (2 * DFF) + (u.pn * 4 + wc) * 64 + (row & 1) * 32 + fq * 8) = pack8(o0, o1); }
	v_pk_mul_f32 v[216:217], v[138:139], v[94:95]
	v_pk_mul_f32 v[218:219], v[138:139], v[96:97]
	v_pk_mul_f32 v[220:221], v[138:139], v[90:91]
	v_pk_mul_f32 v[222:223], v[138:139], v[92:93]
	v_exp_f32_e32 v216, v216
	v_exp_f32_e32 v217, v217
	v_exp_f32_e32 v218, v218
	v_exp_f32_e32 v219, v219
	v_exp_f32_e32 v220, v220
	v_exp_f32_e32 v221, v221
	v_exp_f32_e32 v222, v222
	v_exp_f32_e32 v223, v223
	v_pk_add_f32 v[216:217], v[216:217], 1.0 op_sel_hi:[1,0]
	v_pk_add_f32 v[218:219], v[218:219], 1.0 op_sel_hi:[1,0]
	v_pk_add_f32 v[220:221], v[220:221], 1.0 op_sel_hi:[1,0]
	v_pk_add_f32 v[222:223], v[222:223], 1.0 op_sel_hi:[1,0]
	v_rcp_f32_e32 v216, v216
	v_rcp_f32_e32 v217, v217
	v_rcp_f32_e32 v218, v218
	v_rcp_f32_e32 v219, v219
	v_rcp_f32_e32 v220, v220
	v_rcp_f32_e32 v221, v221
	v_rcp_f32_e32 v222, v222
	v_rcp_f32_e32 v223, v223
	v_pk_mul_f32 v[216:217], v[94:95], v[216:217]
	v_pk_mul_f32 v[218:219], v[96:97], v[218:219]
	v_pk_mul_f32 v[220:221], v[90:91], v[220:221]
	v_pk_mul_f32 v[222:223], v[92:93], v[222:223]
	v_pk_mul_f32 v[216:217], v[216:217], v[86:87]
	v_pk_mul_f32 v[218:219], v[218:219], v[88:89]
	v_pk_mul_f32 v[220:221], v[220:221], v[82:83]
	v_pk_mul_f32 v[222:223], v[222:223], v[84:85]
	v_cvt_pk_bf16_f32 v160, v216, v217
	v_cvt_pk_bf16_f32 v161, v218, v219
	v_cvt_pk_bf16_f32 v162, v220, v221
	v_cvt_pk_bf16_f32 v163, v222, v223
	global_store_dwordx4 v168, v[160:163], s[28:29]
	s_add_u32 s28, s28, 0x16000
	s_addc_u32 s29, s29, 0
	v_pk_fma_f32 v[78:79], v[78:79], v[148:149], v[200:201] op_sel_hi:[1,0,1]
	v_pk_fma_f32 v[80:81], v[80:81], v[148:149], v[202:203] op_sel_hi:[1,0,1]
	v_pk_fma_f32 v[74:75], v[74:75], v[148:149], v[204:205] op_sel_hi:[1,0,1]
	v_pk_fma_f32 v[76:77], v[76:77], v[148:149], v[206:207] op_sel_hi:[1,0,1]
	v_pk_fma_f32 v[70:71], v[70:71], v[148:149], v[208:209] op_sel_hi:[1,0,1]
	v_pk_fma_f32 v[72:73], v[72:73], v[148:149], v[210:211] op_sel_hi:[1,0,1]
	v_pk_fma_f32 v[66:67], v[66:67], v[148:149], v[212:213] op_sel_hi:[1,0,1]
	v_pk_fma_f32 v[68:69], v[68:69], v[148:149], v[214:215] op_sel_hi:[1,0,1]
	v_pk_mul_f32 v[224:225], v[138:139], v[78:79]
	v_pk_mul_f32 v[226:227], v[138:139], v[80:81]
	v_pk_mul_f32 v[228:229], v[138:139], v[74:75]
	v_pk_mul_f32 v[230:231], v[138:139], v[76:77]
	v_exp_f32_e32 v224, v224
	v_exp_f32_e32 v225, v225
	v_exp_f32_e32 v226, v226
	v_exp_f32_e32 v227, v227
	v_exp_f32_e32 v228, v228
	v_exp_f32_e32 v229, v229
	v_exp_f32_e32 v230, v230
	v_exp_f32_e32 v231, v231
	v_pk_add_f32 v[224:225], v[224:225], 1.0 op_sel_hi:[1,0]
	v_pk_add_f32 v[226:227], v[226:227], 1.0 op_sel_hi:[1,0]
	v_pk_add_f32 v[228:229], v[228:229], 1.0 op_sel_hi:[1,0]
	v_pk_add_f32 v[230:231], v[230:231], 1.0 op_sel_hi:[1,0]
	v_rcp_f32_e32 v224, v224
	v_rcp_f32_e32 v225, v225
	v_rcp_f32_e32 v226, v226
	v_rcp_f32_e32 v227, v227
	v_rcp_f32_e32 v228, v228
	v_rcp_f32_e32 v229, v229
	v_rcp_f32_e32 v230, v230
	v_rcp_f32_e32 v231, v231
	v_pk_mul_f32 v[224:225], v[78:79], v[224:225]
	v_pk_mul_f32 v[226:227], v[80:81], v[226:227]
	v_pk_mul_f32 v[228:229], v[74:75], v[228:229]
	v_pk_mul_f32 v[230:231], v[76:77], v[230:231]
	v_pk_mul_f32 v[224:225], v[224:225], v[70:71]
	v_pk_mul_f32 v[226:227], v[226:227], v[72:73]
	v_pk_mul_f32 v[228:229], v[228:229], v[66:67]
	v_pk_mul_f32 v[230:231], v[230:231], v[68:69]
	v_cvt_pk_bf16_f32 v164, v224, v225
	v_cvt_pk_bf16_f32 v165, v226, v227
	v_cvt_pk_bf16_f32 v166, v228, v229
	v_cvt_pk_bf16_f32 v167, v230, v231
	global_store_dwordx4 v168, v[164:167], s[28:29]
	s_add_u32 s28, s28, 0x6e000
	s_addc_u32 s29, s29, 0
	v_pk_fma_f32 v[62:63], v[62:63], v[150:151], v[200:201] op_sel_hi:[1,0,1]
	v_pk_fma_f32 v[64:65], v[64:65], v[150:151], v[202:203] op_sel_hi:[1,0,1]
	v_pk_fma_f32 v[58:59], v[58:59], v[150:151], v[204:205] op_sel_hi:[1,0,1]
	v_pk_fma_f32 v[60:61], v[60:61], v[150:151], v[206:207] op_sel_hi:[1,0,1]
	v_pk_fma_f32 v[54:55], v[54:55], v[150:151], v[208:209] op_sel_hi:[1,0,1]
	v_pk_fma_f32 v[56:57], v[56:57], v[150:151], v[210:211] op_sel_hi:[1,0,1]
	v_pk_fma_f32 v[50:51], v[50:51], v[150:151], v[212:213] op_sel_hi:[1,0,1]
	v_pk_fma_f32 v[52:53], v[52:53], v[150:151], v[214:215] op_sel_hi:[1,0,1]
	v_pk_mul_f32 v[216:217], v[138:139], v[62:63]
	v_pk_mul_f32 v[218:219], v[138:139], v[64:65]
	v_pk_mul_f32 v[220:221], v[138:139], v[58:59]
	v_pk_mul_f32 v[222:223], v[138:139], v[60:61]
	v_exp_f32_e32 v216, v216
	v_exp_f32_e32 v217, v217
	v_exp_f32_e32 v218, v218
	v_exp_f32_e32 v219, v219
	v_exp_f32_e32 v220, v220
	v_exp_f32_e32 v221, v221
	v_exp_f32_e32 v222, v222
	v_exp_f32_e32 v223, v223
	v_pk_add_f32 v[216:217], v[216:217], 1.0 op_sel_hi:[1,0]
	v_pk_add_f32 v[218:219], v[218:219], 1.0 op_sel_hi:[1,0]
	v_pk_add_f32 v[220:221], v[220:221], 1.0 op_sel_hi:[1,0]
	v_pk_add_f32 v[222:223], v[222:223], 1.0 op_sel_hi:[1,0]
	v_rcp_f32_e32 v216, v216
	v_rcp_f32_e32 v217, v217
	v_rcp_f32_e32 v218, v218
	v_rcp_f32_e32 v219, v219
	v_rcp_f32_e32 v220, v220
	v_rcp_f32_e32 v221, v221
	v_rcp_f32_e32 v222, v222
	v_rcp_f32_e32 v223, v223
	v_pk_mul_f32 v[216:217], v[62:63], v[216:217]
	v_pk_mul_f32 v[218:219], v[64:65], v[218:219]
	v_pk_mul_f32 v[220:221], v[58:59], v[220:221]
	v_pk_mul_f32 v[222:223], v[60:61], v[222:223]
	v_pk_mul_f32 v[216:217], v[216:217], v[54:55]
	v_pk_mul_f32 v[218:219], v[218:219], v[56:57]
	v_pk_mul_f32 v[220:221], v[220:221], v[50:51]
	v_pk_mul_f32 v[222:223], v[222:223], v[52:53]
	v_cvt_pk_bf16_f32 v160, v216, v217
	v_cvt_pk_bf16_f32 v161, v218, v219
	v_cvt_pk_bf16_f32 v162, v220, v221
	v_cvt_pk_bf16_f32 v163, v222, v223
	global_store_dwordx4 v168, v[160:163], s[28:29]
	s_add_u32 s28, s28, 0x16000
	s_addc_u32 s29, s29, 0
	v_pk_fma_f32 v[46:47], v[46:47], v[152:153], v[200:201] op_sel_hi:[1,0,1]
; __device__ __forceinline__ u32x4 pack8(const f32x4 a, const f32x4 b) { u32x4 w; w.x = cvt_pk_bf16(a[0], a[1]); w.y = cvt_pk_bf16(a[2], a[3]); w.z = cvt_pk_bf16(b[0], b[1]); w.w = cvt_pk_bf16(b[2], b[3]); return w; }
; __device__ __forceinline__ float sigm(float v) { return __builtin_amdgcn_rcpf(1.f + __expf(-v)); }
; #define EPI_ROWS _Pragma("unroll") for (int ai = 0; ai < 2; ++ai) _Pragma("unroll") for (int m = 0; m < 4; ++m)
;     __device__ __forceinline__ void operator()(const f32x4 (&acc)[2][2][4][2], const Unit& u, int wr, int wc, int fr, int fq) const {
;     ...
;         EPI_ROWS { const int row = EPI_ROW;
;             f32x4 a0 = acc[ai][0][m][0], a1 = acc[ai][0][m][1], b0 = acc[ai][1][m][0], b1 = acc[ai][1][m][1];
;             if (NORM) { const float rs = rsv[ai][m]; a0 = a0 * rs + ba0; a1 = a1 * rs + ba1; b0 = b0 * rs + bb0; b1 = b1 * rs + bb1; }
;             f32x4 o0, o1;
; #pragma unroll
;             for (int i = 0; i < 4; ++i) { o0[i] = a0[i] * sigm(a0[i]) * b0[i]; o1[i] = a1[i] * sigm(a1[i]) * b1[i]; }
;             *(u32x4*)(act + (size_t)(row >> 1) * (2 * DFF) + (u.pn * 4 + wc) * 64 + (row & 1) * 32 + fq * 8) = pack8(o0, o1); }
	v_pk_fma_f32 v[48:49], v[48:49], v[152:153], v[202:203] op_sel_hi:[1,0,1]
	v_pk_fma_f32 v[42:43], v[42:43], v[152:153], v[204:205] op_sel_hi:[1,0,1]
	v_pk_fma_f32 v[44:45], v[44:45], v[152:153], v[206:207] op_sel_hi:[1,0,1]
	v_pk_fma_f32 v[38:39], v[38:39], v[152:153], v[208:209] op_sel_hi:[1,0,1]
	v_pk_fma_f32 v[40:41], v[40:41], v[152:153], v[210:211] op_sel_hi:[1,0,1]
	v_pk_fma_f32 v[34:35], v[34:35], v[152:153], v[212:213] op_sel_hi:[1,0,1]
	v_pk_fma_f32 v[36:37], v[36:37], v[152:153], v[214:215] op_sel_hi:[1,0,1]
	v_pk_mul_f32 v[224:225], v[138:139], v[46:47]
	v_pk_mul_f32 v[226:227], v[138:139], v[48:49]
	v_pk_mul_f32 v[228:229], v[138:139], v[42:43]
	v_pk_mul_f32 v[230:231], v[138:139], v[44:45]
	v_exp_f32_e32 v224, v224
	v_exp_f32_e32 v225, v225
	v_exp_f32_e32 v226, v226
	v_exp_f32_e32 v227, v227
	v_exp_f32_e32 v228, v228
	v_exp_f32_e32 v229, v229
	v_exp_f32_e32 v230, v230
	v_exp_f32_e32 v231, v231
	v_pk_add_f32 v[224:225], v[224:225], 1.0 op_sel_hi:[1,0]
	v_pk_add_f32 v[226:227], v[226:227], 1.0 op_sel_hi:[1,0]
	v_pk_add_f32 v[228:229], v[228:229], 1.0 op_sel_hi:[1,0]
	v_pk_add_f32 v[230:231], v[230:231], 1.0 op_sel_hi:[1,0]
	v_rcp_f32_e32 v224, v224
	v_rcp_f32_e32 v225, v225
	v_rcp_f32_e32 v226, v226
	v_rcp_f32_e32 v227, v227
	v_rcp_f32_e32 v228, v228
	v_rcp_f32_e32 v229, v229
	v_rcp_f32_e32 v230, v230
	v_rcp_f32_e32 v231, v231
	v_pk_mul_f32 v[224:225], v[46:47], v[224:225]
	v_pk_mul_f32 v[226:227], v[48:49], v[226:227]
	v_pk_mul_f32 v[228:229], v[42:43], v[228:229]
	v_pk_mul_f32 v[230:231], v[44:45], v[230:231]
	v_pk_mul_f32 v[224:225], v[224:225], v[38:39]
	v_pk_mul_f32 v[226:227], v[226:227], v[40:41]
	v_pk_mul_f32 v[228:229], v[228:229], v[34:35]
	v_pk_mul_f32 v[230:231], v[230:231], v[36:37]
	v_cvt_pk_bf16_f32 v164, v224, v225
	v_cvt_pk_bf16_f32 v165, v226, v227
	v_cvt_pk_bf16_f32 v166, v228, v229
	v_cvt_pk_bf16_f32 v167, v230, v231
	global_store_dwordx4 v168, v[164:167], s[28:29]
	s_add_u32 s28, s28, 0x16000
	s_addc_u32 s29, s29, 0
	v_pk_fma_f32 v[30:31], v[30:31], v[154:155], v[200:201] op_sel_hi:[1,0,1]
	v_pk_fma_f32 v[32:33], v[32:33], v[154:155], v[202:203] op_sel_hi:[1,0,1]
	v_pk_fma_f32 v[26:27], v[26:27], v[154:155], v[204:205] op_sel_hi:[1,0,1]
	v_pk_fma_f32 v[28:29], v[28:29], v[154:155], v[206:207] op_sel_hi:[1,0,1]
	v_pk_fma_f32 v[22:23], v[22:23], v[154:155], v[208:209] op_sel_hi:[1,0,1]
	v_pk_fma_f32 v[24:25], v[24:25], v[154:155], v[210:211] op_sel_hi:[1,0,1]
	v_pk_fma_f32 v[18:19], v[18:19], v[154:155], v[212:213] op_sel_hi:[1,0,1]
	v_pk_fma_f32 v[20:21], v[20:21], v[154:155], v[214:215] op_sel_hi:[1,0,1]
	v_pk_mul_f32 v[216:217], v[138:139], v[30:31]
	v_pk_mul_f32 v[218:219], v[138:139], v[32:33]
	v_pk_mul_f32 v[220:221], v[138:139], v[26:27]
	v_pk_mul_f32 v[222:223], v[138:139], v[28:29]
	v_exp_f32_e32 v216, v216
	v_exp_f32_e32 v217, v217
	v_exp_f32_e32 v218, v218
	v_exp_f32_e32 v219, v219
	v_exp_f32_e32 v220, v220
	v_exp_f32_e32 v221, v221
	v_exp_f32_e32 v222, v222
	v_exp_f32_e32 v223, v223
	v_pk_add_f32 v[216:217], v[216:217], 1.0 op_sel_hi:[1,0]
	v_pk_add_f32 v[218:219], v[218:219], 1.0 op_sel_hi:[1,0]
	v_pk_add_f32 v[220:221], v[220:221], 1.0 op_sel_hi:[1,0]
	v_pk_add_f32 v[222:223], v[222:223], 1.0 op_sel_hi:[1,0]
	v_rcp_f32_e32 v216, v216
	v_rcp_f32_e32 v217, v217
	v_rcp_f32_e32 v218, v218
	v_rcp_f32_e32 v219, v219
	v_rcp_f32_e32 v220, v220
	v_rcp_f32_e32 v221, v221
	v_rcp_f32_e32 v222, v222
	v_rcp_f32_e32 v223, v223
	v_pk_mul_f32 v[216:217], v[30:31], v[216:217]
	v_pk_mul_f32 v[218:219], v[32:33], v[218:219]
	v_pk_mul_f32 v[220:221], v[26:27], v[220:221]
	v_pk_mul_f32 v[222:223], v[28:29], v[222:223]
	v_pk_mul_f32 v[216:217], v[216:217], v[22:23]
	v_pk_mul_f32 v[218:219], v[218:219], v[24:25]
	v_pk_mul_f32 v[220:221], v[220:221], v[18:19]
	v_pk_mul_f32 v[222:223], v[222:223], v[20:21]
	v_cvt_pk_bf16_f32 v160, v216, v217
	v_cvt_pk_bf16_f32 v161, v218, v219
	v_cvt_pk_bf16_f32 v162, v220, v221
	v_cvt_pk_bf16_f32 v163, v222, v223
	global_store_dwordx4 v168, v[160:163], s[28:29]
	s_add_u32 s28, s28, 0x16000
	s_addc_u32 s29, s29, 0
	v_pk_fma_f32 v[14:15], v[14:15], v[156:157], v[200:201] op_sel_hi:[1,0,1]
	v_pk_fma_f32 v[16:17], v[16:17], v[156:157], v[202:203] op_sel_hi:[1,0,1]
	v_pk_fma_f32 v[10:11], v[10:11], v[156:157], v[204:205] op_sel_hi:[1,0,1]
	v_pk_fma_f32 v[12:13], v[12:13], v[156:157], v[206:207] op_sel_hi:[1,0,1]
	v_pk_fma_f32 v[6:7], v[6:7], v[156:157], v[208:209] op_sel_hi:[1,0,1]
	v_pk_fma_f32 v[8:9], v[8:9], v[156:157], v[210:211] op_sel_hi:[1,0,1]
	v_pk_fma_f32 v[2:3], v[2:3], v[156:157], v[212:213] op_sel_hi:[1,0,1]
	v_pk_fma_f32 v[4:5], v[4:5], v[156:157], v[214:215] op_sel_hi:[1,0,1]
	v_pk_mul_f32 v[224:225], v[138:139], v[14:15]
	v_pk_mul_f32 v[226:227], v[138:139], v[16:17]
	v_pk_mul_f32 v[228:229], v[138:139], v[10:11]
	v_pk_mul_f32 v[230:231], v[138:139], v[12:13]
	v_exp_f32_e32 v224, v224
	v_exp_f32_e32 v225, v225
	v_exp_f32_e32 v226, v226
	v_exp_f32_e32 v227, v227
	v_exp_f32_e32 v228, v228
	v_exp_f32_e32 v229, v229
	v_exp_f32_e32 v230, v230
	v_exp_f32_e32 v231, v231
	v_pk_add_f32 v[224:225], v[224:225], 1.0 op_sel_hi:[1,0]
	v_pk_add_f32 v[226:227], v[226:227], 1.0 op_sel_hi:[1,0]
	v_pk_add_f32 v[228:229], v[228:229], 1.0 op_sel_hi:[1,0]
	v_pk_add_f32 v[230:231], v[230:231], 1.0 op_sel_hi:[1,0]
	v_rcp_f32_e32 v224, v224
	v_rcp_f32_e32 v225, v225
	v_rcp_f32_e32 v226, v226
	v_rcp_f32_e32 v227, v227
	v_rcp_f32_e32 v228, v228
	v_rcp_f32_e32 v229, v229
	v_rcp_f32_e32 v230, v230
	v_rcp_f32_e32 v231, v231
	v_pk_mul_f32 v[224:225], v[14:15], v[224:225]
	v_pk_mul_f32 v[226:227], v[16:17], v[226:227]
	v_pk_mul_f32 v[228:229], v[10:11], v[228:229]
	v_pk_mul_f32 v[230:231], v[12:13], v[230:231]
	v_pk_mul_f32 v[224:225], v[224:225], v[6:7]
	v_pk_mul_f32 v[226:227], v[226:227], v[8:9]
	v_pk_mul_f32 v[228:229], v[228:229], v[2:3]
	v_pk_mul_f32 v[230:231], v[230:231], v[4:5]
	v_cvt_pk_bf16_f32 v164, v224, v225
	v_cvt_pk_bf16_f32 v165, v226, v227
	v_cvt_pk_bf16_f32 v166, v228, v229
	v_cvt_pk_bf16_f32 v167, v230, v231
	s_andn2_b64 vcc, exec, s[2:3]
	s_mov_b64 s[2:3], -1
	global_store_dwordx4 v168, v[164:167], s[28:29]
	s_cbranch_vccnz .LBB0_981
	s_andn2_b64 vcc, exec, s[4:5]
	s_cbranch_vccnz .LBB0_980
	s_barrier
	s_branch .LBB0_980
